# static s_setprio 1 for the second-arriving (role-1) block of each CU during the four GEMM phases (lever 4), on top of last-barrier elimination
# baseline (speedup 1.0000x reference)
.LBB0_277:
	s_or_b64 exec, exec, s[0:1]
	s_and_b32 s0, s33, 1
	s_bitcmp1_b32 s33, 0
	s_cselect_b64 s[2:3], -1, 0
	v_writelane_b32 v246, s2, 26
	s_cmp_eq_u32 s0, 0
	s_waitcnt lgkmcnt(0)
	s_barrier
	v_writelane_b32 v246, s3, 27
	s_cbranch_scc1 .LBB0_279
	s_sleep 22
	s_setprio 1

.LBB0_330:
	s_setprio 0
	s_waitcnt vmcnt(0)
	v_readlane_b32 s24, v247, 10
	v_readlane_b32 s25, v247, 11
	s_barrier
	s_and_saveexec_b64 s[0:1], s[24:25]
	s_cbranch_execz .LBB0_382
	v_mov_b32_e32 v0, 0x13800
	s_waitcnt vmcnt(0) expcnt(0) lgkmcnt(0)
	ds_read_b32 v2, v0
	v_mov_b32_e32 v0, 0x13804
	ds_read_b32 v0, v0
	s_waitcnt lgkmcnt(1)
	v_cmp_ne_u32_e32 vcc, 0, v2
	s_cbranch_vccnz .LBB0_346
	v_readlane_b32 s4, v247, 2
	v_readlane_b32 s11, v247, 9
	v_readlane_b32 s2, v247, 12
	s_mul_i32 s16, s11, s2
	s_add_u32 s2, s60, 0x1000
	s_addc_u32 s3, s61, 0
	v_readlane_b32 s5, v247, 3
	s_add_u32 s4, s60, 0x1100
	v_readlane_b32 s6, v247, 4
	s_addc_u32 s5, s61, 0
	v_readlane_b32 s7, v247, 5
	s_add_u32 s6, s60, 0x1200
	v_readlane_b32 s8, v247, 6
	s_addc_u32 s7, s61, 0
	v_readlane_b32 s9, v247, 7
	v_readlane_b32 s10, v247, 8
	s_add_u32 s8, s60, 0x1300
	s_mul_i32 s16, s16, s10
	s_addc_u32 s9, s61, 0
	s_mov_b32 s17, 1
	v_mov_b32_e32 v16, 0
	s_branch .LBB0_334

.LBB0_698:
	s_or_b64 exec, exec, s[0:1]
	v_readlane_b32 s0, v246, 26
	v_readlane_b32 s1, v246, 27
	s_andn2_b64 vcc, exec, s[0:1]
	s_waitcnt lgkmcnt(0)
	v_cndmask_b32_e64 v0, 0, 1, s[0:1]
	v_cmp_ne_u32_e64 s[6:7], 1, v0
	s_barrier
	s_cbranch_vccnz .LBB0_700
	s_sleep 22
	s_setprio 1

.LBB0_711:
	s_setprio 0
	s_waitcnt vmcnt(0)
	s_barrier
	s_and_saveexec_b64 s[2:3], s[60:61]
	s_cbranch_execz .LBB0_763
	v_mov_b32_e32 v0, 0x13800
	s_waitcnt vmcnt(0) expcnt(0) lgkmcnt(0)
	ds_read_b32 v2, v0
	v_mov_b32_e32 v0, 0x13804
	ds_read_b32 v0, v0
	s_waitcnt lgkmcnt(1)
	v_cmp_ne_u32_e32 vcc, 0, v2
	s_cbranch_vccnz .LBB0_727
	v_readlane_b32 s8, v247, 2
	v_readlane_b32 s15, v247, 9
	v_readlane_b32 s4, v247, 12
	s_mul_i32 s20, s15, s4
	s_add_u32 s4, s64, 0x1000
	s_addc_u32 s5, s65, 0
	v_readlane_b32 s9, v247, 3
	s_add_u32 s8, s64, 0x1100
	v_readlane_b32 s10, v247, 4
	s_addc_u32 s9, s65, 0
	v_readlane_b32 s11, v247, 5
	s_add_u32 s10, s64, 0x1200
	v_readlane_b32 s12, v247, 6
	s_addc_u32 s11, s65, 0
	v_readlane_b32 s13, v247, 7
	v_readlane_b32 s14, v247, 8
	s_add_u32 s12, s64, 0x1300
	s_mul_i32 s20, s20, s14
	s_addc_u32 s13, s65, 0
	s_mov_b32 s21, 1
	v_mov_b32_e32 v16, 0
	s_branch .LBB0_715

.LBB0_763:
	s_or_b64 exec, exec, s[2:3]
	s_and_b64 vcc, exec, s[6:7]
	s_waitcnt lgkmcnt(0)
	s_barrier
	s_cbranch_vccnz .LBB0_765
	s_sleep 22
	s_setprio 1

.LBB0_772:
	s_setprio 0
	s_waitcnt vmcnt(0)
	s_barrier
	s_and_saveexec_b64 s[0:1], s[60:61]
	s_cbranch_execz .LBB0_824
	v_mov_b32_e32 v0, 0x13800
	s_waitcnt vmcnt(0) expcnt(0) lgkmcnt(0)
	ds_read_b32 v2, v0
	v_mov_b32_e32 v0, 0x13804
	ds_read_b32 v0, v0
	s_waitcnt lgkmcnt(1)
	v_cmp_ne_u32_e32 vcc, 0, v2
	s_cbranch_vccnz .LBB0_788
	v_readlane_b32 s8, v247, 2
	v_readlane_b32 s15, v247, 9
	v_readlane_b32 s2, v247, 12
	s_mul_i32 s18, s15, s2
	s_add_u32 s2, s64, 0x1000
	s_addc_u32 s3, s65, 0
	s_add_u32 s4, s64, 0x1100
	s_addc_u32 s5, s65, 0
	v_readlane_b32 s9, v247, 3
	s_add_u32 s8, s64, 0x1200
	v_readlane_b32 s10, v247, 4
	s_addc_u32 s9, s65, 0
	v_readlane_b32 s11, v247, 5
	v_readlane_b32 s14, v247, 8
	s_add_u32 s10, s64, 0x1300
	s_mul_i32 s18, s18, s14
	s_addc_u32 s11, s65, 0
	s_mov_b32 s19, 1
	v_mov_b32_e32 v16, 0
	v_readlane_b32 s12, v247, 6
	v_readlane_b32 s13, v247, 7
	s_branch .LBB0_776

.LBB0_881:
	s_or_b64 exec, exec, s[0:1]
	s_and_b64 vcc, exec, s[6:7]
	s_waitcnt lgkmcnt(0)
	s_barrier
	s_cbranch_vccnz .LBB0_883
	s_sleep 22
	s_setprio 1

.LBB0_890:
	s_setprio 0
	s_waitcnt vmcnt(0)
	s_barrier
	s_and_saveexec_b64 s[0:1], s[60:61]
	s_cbranch_execz .LBB0_942
	v_mov_b32_e32 v0, 0x13800
	s_waitcnt vmcnt(0) expcnt(0) lgkmcnt(0)
	ds_read_b32 v2, v0
	v_mov_b32_e32 v0, 0x13804
	ds_read_b32 v0, v0
	s_waitcnt lgkmcnt(1)
	v_cmp_ne_u32_e32 vcc, 0, v2
	s_cbranch_vccnz .LBB0_906
	v_readlane_b32 s4, v247, 2
	v_readlane_b32 s11, v247, 9
	v_readlane_b32 s2, v247, 12
	s_mul_i32 s16, s11, s2
	s_add_u32 s2, s64, 0x1000
	s_addc_u32 s3, s65, 0
	v_readlane_b32 s5, v247, 3
	s_add_u32 s4, s64, 0x1100
	v_readlane_b32 s6, v247, 4
	s_addc_u32 s5, s65, 0
	v_readlane_b32 s7, v247, 5
	s_add_u32 s6, s64, 0x1200
	v_readlane_b32 s8, v247, 6
	s_addc_u32 s7, s65, 0
	v_readlane_b32 s9, v247, 7
	v_readlane_b32 s10, v247, 8
	s_add_u32 s8, s64, 0x1300
	s_mul_i32 s16, s16, s10
	s_addc_u32 s9, s65, 0
	s_mov_b32 s17, 1
	v_mov_b32_e32 v16, 0
	s_branch .LBB0_894
